# hand-scheduled fast path for unmasked tiles in MLA and FoX main loops: per-32-key-half online softmax, QK(kb1) MFMAs interleaved with softmax(kb0) VALU, PV MFMAs interleaved with softmax(kb1)
# baseline (speedup 1.0000x reference)
; template <int MODE>
; __device__ __forceinline__ void attn_unit(const Params& P, int b, int h, int qb, unsigned char* smem) {
;     ...
;         for (int ks = 0; ks < 4; ++ks) {
;           bf16x8 kf = *(const bf16x8*)(smem + cur + (32 * kb + r) * 128 + (((2 * ks + hi) ^ swz) << 4));
;           sacc[kb] = __builtin_amdgcn_mfma_f32_32x32x16_bf16(kf, qf[ks], sacc[kb], 0, 0, 0);
;         }
;         if (MODE == 0) {
; #pragma unroll
;           for (int ks = 0; ks < 2; ++ks) {
;             bf16x8 kf = *(const bf16x8*)(smem + cur + 16384 + (32 * kb + r) * 64 + (((2 * ks + hi) ^ swr) << 4));
;             sacc[kb] = __builtin_amdgcn_mfma_f32_32x32x16_bf16(kf, qf[4 + ks], sacc[kb], 0, 0, 0);
;           }
;         }
;       }
;       if (MODE == 2) {
; #pragma unroll
;         for (int kb = 0; kb < 2; ++kb)
; #pragma unroll
;           for (int i = 0; i < 16; ++i) {
;             const int key = k0 + 32 * kb + 8 * (i >> 2) + 4 * hi + (i & 3);
;             const int dist = qi - key;
;             const float v = sacc[kb][i] - slope2 * (float)dist;
;             sacc[kb][i] = (dist >= 0 && dist < 128) ? v : -INFINITY;
;           }
;       } else if (k0 + 63 > qw0) {
; #pragma unroll
;         for (int kb = 0; kb < 2; ++kb)
; #pragma unroll
;           for (int i = 0; i < 16; ++i) {
;             const int key = k0 + 32 * kb + 8 * (i >> 2) + 4 * hi + (i & 3);
;             if (key > qi) sacc[kb][i] = -INFINITY;
;           }
;       }
.LBB0_848:
	s_or_b64 exec, exec, s[16:17]
	s_bitcmp1_b32 s27, 0
	s_cselect_b32 s28, 0x5100, 0
	v_cmp_le_i32_e32 vcc, s10, v92
	s_and_saveexec_b64 s[16:17], vcc
	s_cbranch_execz .LBB0_854
	s_add_i32 s18, s28, 0
	v_add_u32_e32 v11, s18, v153
	v_add_u32_e32 v13, s18, v148
	v_add_u32_e32 v10, v11, v155
	v_add_u32_e32 v0, v11, v154
	v_add_u32_e32 v12, v11, v152
	v_add_u32_e32 v11, v11, v151
	v_add_u32_e32 v14, v13, v149
	v_add_u32_e32 v13, v13, v150
	ds_read_b128 v[192:195], v10
	ds_read_b128 v[172:175], v0
	ds_read_b128 v[176:179], v12
	ds_read_b128 v[180:183], v11
	ds_read_b128 v[184:187], v14 offset:16384
	ds_read_b128 v[188:191], v13 offset:16384
	ds_read_b128 v[48:51], v10 offset:4096
	ds_read_b128 v[94:97], v0 offset:4096
	ds_read_b128 v[98:101], v12 offset:4096
	ds_read_b128 v[102:105], v11 offset:4096
	ds_read_b128 v[106:109], v14 offset:18432
	ds_read_b128 v[158:161], v13 offset:18432
	s_add_i32 s18, s10, 63
	v_cmp_gt_i32_e32 vcc, s18, v146
	s_cbranch_vccz .Lmla_fast
	s_waitcnt lgkmcnt(11)
	v_mfma_f32_32x32x16_bf16 v[64:79], v[192:195], v[118:121], 0
	s_waitcnt lgkmcnt(10)
	v_mfma_f32_32x32x16_bf16 v[64:79], v[172:175], v[122:125], v[64:79]
	s_waitcnt lgkmcnt(9)
	v_mfma_f32_32x32x16_bf16 v[64:79], v[176:179], v[126:129], v[64:79]
	s_waitcnt lgkmcnt(8)
	v_mfma_f32_32x32x16_bf16 v[64:79], v[180:183], v[130:133], v[64:79]
	s_waitcnt lgkmcnt(7)
	v_mfma_f32_32x32x16_bf16 v[64:79], v[184:187], v[134:137], v[64:79]
	s_waitcnt lgkmcnt(6)
	v_mfma_f32_32x32x16_bf16 v[64:79], v[188:191], v[114:117], v[64:79]
	s_waitcnt lgkmcnt(5)
	v_mfma_f32_32x32x16_bf16 v[48:63], v[48:51], v[118:121], 0
	s_waitcnt lgkmcnt(4)
	v_mfma_f32_32x32x16_bf16 v[48:63], v[94:97], v[122:125], v[48:63]
	s_waitcnt lgkmcnt(3)
	v_mfma_f32_32x32x16_bf16 v[48:63], v[98:101], v[126:129], v[48:63]
	s_waitcnt lgkmcnt(2)
	v_mfma_f32_32x32x16_bf16 v[48:63], v[102:105], v[130:133], v[48:63]
	s_waitcnt lgkmcnt(1)
	v_mfma_f32_32x32x16_bf16 v[48:63], v[106:109], v[134:137], v[48:63]
	s_waitcnt lgkmcnt(0)
	v_mfma_f32_32x32x16_bf16 v[48:63], v[158:161], v[114:117], v[48:63]
	s_and_saveexec_b64 s[18:19], vcc
	s_cbranch_execz .LBB0_851
	v_add_u32_e32 v13, s10, v144
	v_cmp_gt_i32_e32 vcc, v13, v140
	s_nop 1
	v_cndmask_b32_e32 v14, v64, v143, vcc
	v_cmp_lt_i32_e32 vcc, v13, v140
	s_nop 1
	v_cndmask_b32_e32 v64, v14, v64, vcc
	v_add_u32_e32 v14, 2, v13
	v_cndmask_b32_e32 v65, v143, v65, vcc
	v_cmp_le_i32_e32 vcc, v14, v140
	v_add_u32_e32 v14, 3, v13
	s_nop 0
	v_cndmask_b32_e32 v66, v143, v66, vcc
	v_cmp_le_i32_e32 vcc, v14, v140
	v_add_u32_e32 v14, 8, v13
	s_nop 0
	v_cndmask_b32_e32 v67, v143, v67, vcc
	v_cmp_le_i32_e32 vcc, v14, v140
	v_add_u32_e32 v14, 9, v13
	s_nop 0
	v_cndmask_b32_e32 v68, v143, v68, vcc
	v_cmp_le_i32_e32 vcc, v14, v140
	v_add_u32_e32 v14, 10, v13
	s_nop 0
	v_cndmask_b32_e32 v69, v143, v69, vcc
	v_cmp_le_i32_e32 vcc, v14, v140
	v_add_u32_e32 v14, 11, v13
	s_nop 0
	v_cndmask_b32_e32 v70, v143, v70, vcc
	v_cmp_le_i32_e32 vcc, v14, v140
	v_add_u32_e32 v14, 16, v13
	s_nop 0
	v_cndmask_b32_e32 v71, v143, v71, vcc
	v_cmp_le_i32_e32 vcc, v14, v140
	v_add_u32_e32 v14, 17, v13
	s_nop 0
	v_cndmask_b32_e32 v72, v143, v72, vcc
	v_cmp_le_i32_e32 vcc, v14, v140
	v_add_u32_e32 v14, 18, v13
	s_nop 0
	v_cndmask_b32_e32 v73, v143, v73, vcc
	v_cmp_le_i32_e32 vcc, v14, v140
	v_add_u32_e32 v14, 19, v13
	s_nop 0
	v_cndmask_b32_e32 v74, v143, v74, vcc
	v_cmp_le_i32_e32 vcc, v14, v140
	v_add_u32_e32 v14, 24, v13
	s_nop 0
	v_cndmask_b32_e32 v75, v143, v75, vcc
	v_cmp_le_i32_e32 vcc, v14, v140
	v_add_u32_e32 v14, 25, v13
	s_nop 0
	v_cndmask_b32_e32 v76, v143, v76, vcc
	v_cmp_le_i32_e32 vcc, v14, v140
	v_add_u32_e32 v14, 26, v13
	s_nop 0
	v_cndmask_b32_e32 v77, v143, v77, vcc
	v_cmp_le_i32_e32 vcc, v14, v140
	v_add_u32_e32 v14, 27, v13
	s_nop 0
	v_cndmask_b32_e32 v78, v143, v78, vcc
	v_cmp_le_i32_e32 vcc, v14, v140
	v_add_u32_e32 v14, 32, v13
	s_nop 0
	v_cndmask_b32_e32 v79, v143, v79, vcc
	v_cmp_le_i32_e32 vcc, v14, v140
	v_add_u32_e32 v14, 33, v13
	s_nop 0
	v_cndmask_b32_e32 v48, v143, v48, vcc
	v_cmp_le_i32_e32 vcc, v14, v140
	v_add_u32_e32 v14, 34, v13
	s_nop 0
	v_cndmask_b32_e32 v49, v143, v49, vcc
	v_cmp_le_i32_e32 vcc, v14, v140
	v_add_u32_e32 v14, 35, v13
	s_nop 0
	v_cndmask_b32_e32 v50, v143, v50, vcc
	v_cmp_le_i32_e32 vcc, v14, v140
	v_add_u32_e32 v14, 40, v13
	s_nop 0
	v_cndmask_b32_e32 v51, v143, v51, vcc
	v_cmp_le_i32_e32 vcc, v14, v140
	v_add_u32_e32 v14, 41, v13
	s_nop 0
	v_cndmask_b32_e32 v52, v143, v52, vcc
	v_cmp_le_i32_e32 vcc, v14, v140
	v_add_u32_e32 v14, 42, v13
	s_nop 0
	v_cndmask_b32_e32 v53, v143, v53, vcc
	v_cmp_le_i32_e32 vcc, v14, v140
	v_add_u32_e32 v14, 43, v13
	s_nop 0
	v_cndmask_b32_e32 v54, v143, v54, vcc
	v_cmp_le_i32_e32 vcc, v14, v140
	v_add_u32_e32 v14, 48, v13
	s_nop 0
	v_cndmask_b32_e32 v55, v143, v55, vcc
	v_cmp_le_i32_e32 vcc, v14, v140
	v_add_u32_e32 v14, 49, v13
	s_nop 0
	v_cndmask_b32_e32 v56, v143, v56, vcc
	v_cmp_le_i32_e32 vcc, v14, v140
	v_add_u32_e32 v14, 50, v13
	s_nop 0
	v_cndmask_b32_e32 v57, v143, v57, vcc
	v_cmp_le_i32_e32 vcc, v14, v140
	v_add_u32_e32 v14, 51, v13
	s_nop 0
	v_cndmask_b32_e32 v58, v143, v58, vcc
	v_cmp_le_i32_e32 vcc, v14, v140
	v_add_u32_e32 v14, 56, v13
	s_nop 0
	v_cndmask_b32_e32 v59, v143, v59, vcc
	v_cmp_le_i32_e32 vcc, v14, v140
	v_add_u32_e32 v14, 57, v13
	s_nop 0
	v_cndmask_b32_e32 v60, v143, v60, vcc
	v_cmp_le_i32_e32 vcc, v14, v140
	v_add_u32_e32 v14, 58, v13
	v_add_u32_e32 v13, 59, v13
	v_cndmask_b32_e32 v61, v143, v61, vcc
	v_cmp_le_i32_e32 vcc, v14, v140
	s_nop 1
	v_cndmask_b32_e32 v62, v143, v62, vcc
	v_cmp_le_i32_e32 vcc, v13, v140
	s_nop 1
	v_cndmask_b32_e32 v63, v143, v63, vcc

; template <int MODE>
; __device__ __forceinline__ void attn_unit(const Params& P, int b, int h, int qb, unsigned char* smem) {
;     ...
;         for (int ks = 0; ks < 4; ++ks) {
;           bf16x8 kf = *(const bf16x8*)(smem + cur + (32 * kb + r) * 128 + (((2 * ks + hi) ^ swz) << 4));
;           sacc[kb] = __builtin_amdgcn_mfma_f32_32x32x16_bf16(kf, qf[ks], sacc[kb], 0, 0, 0);
;         }
;         if (MODE == 0) {
; #pragma unroll
;           for (int ks = 0; ks < 2; ++ks) {
;             bf16x8 kf = *(const bf16x8*)(smem + cur + 16384 + (32 * kb + r) * 64 + (((2 * ks + hi) ^ swr) << 4));
;             sacc[kb] = __builtin_amdgcn_mfma_f32_32x32x16_bf16(kf, qf[4 + ks], sacc[kb], 0, 0, 0);
;           }
;         }
;       }
;       if (MODE == 2) {
; #pragma unroll
;         for (int kb = 0; kb < 2; ++kb)
; #pragma unroll
;           for (int i = 0; i < 16; ++i) {
;             const int key = k0 + 32 * kb + 8 * (i >> 2) + 4 * hi + (i & 3);
;             const int dist = qi - key;
;             const float v = sacc[kb][i] - slope2 * (float)dist;
;             sacc[kb][i] = (dist >= 0 && dist < 128) ? v : -INFINITY;
;           }
;       } else if (k0 + 63 > qw0) {
; #pragma unroll
;         for (int kb = 0; kb < 2; ++kb)
; #pragma unroll
;           for (int i = 0; i < 16; ++i) {
;             const int key = k0 + 32 * kb + 8 * (i >> 2) + 4 * hi + (i & 3);
;             if (key > qi) sacc[kb][i] = -INFINITY;
;           }
;       }
;       float mx = sacc[0][0];
; #pragma unroll
;       for (int i = 1; i < 16; ++i) mx = fmaxf(mx, sacc[0][i]);
; #pragma unroll
;       for (int i = 0; i < 16; ++i) mx = fmaxf(mx, sacc[1][i]);
;       mx = fmaxf(mx, __shfl_xor(mx, 32));
;       if (__any(mx > m_run + 24.0f)) {
;         const float m_new = fmaxf(m_run, mx);
;         const float alpha = fast_exp2(m_run - m_new);
;         m_run = m_new; l_run *= alpha;
;         const f32x2_t a2 = {alpha, alpha};
; #pragma unroll
;         for (int i = 0; i < 8; ++i) {
;           f32x2_t t0 = {oacc[0][2 * i], oacc[0][2 * i + 1]}, t1 = {oacc[1][2 * i], oacc[1][2 * i + 1]};
;           t0 *= a2; t1 *= a2;
;           oacc[0][2 * i] = t0[0]; oacc[0][2 * i + 1] = t0[1]; oacc[1][2 * i] = t1[0]; oacc[1][2 * i + 1] = t1[1];
;         }
;       }
;       {
;         const f32x2_t m2 = {m_run, m_run};
;         f32x2_t ps2 = {0.f, 0.f};
; #pragma unroll
.Lmla_fast:
	v_add_f32_e32 v162, 0x41c00000, v142
	s_waitcnt lgkmcnt(11)
	v_mfma_f32_32x32x16_bf16 v[64:79], v[192:195], v[118:121], 0
	ds_read_b128 v[212:215], v10 offset:8192
	ds_read_b128 v[228:231], v10 offset:12288
	ds_read_b128 v[216:219], v0 offset:8192
	ds_read_b128 v[232:235], v0 offset:12288
	s_waitcnt lgkmcnt(14)
	v_mfma_f32_32x32x16_bf16 v[64:79], v[172:175], v[122:125], v[64:79]
	ds_read_b128 v[220:223], v12 offset:8192
	s_waitcnt lgkmcnt(14)
	v_mfma_f32_32x32x16_bf16 v[64:79], v[176:179], v[126:129], v[64:79]
	ds_read_b128 v[236:239], v12 offset:12288
	s_waitcnt lgkmcnt(14)
	v_mfma_f32_32x32x16_bf16 v[64:79], v[180:183], v[130:133], v[64:79]
	ds_read_b128 v[224:227], v11 offset:8192
	s_waitcnt lgkmcnt(14)
	v_mfma_f32_32x32x16_bf16 v[64:79], v[184:187], v[134:137], v[64:79]
	ds_read_b128 v[240:243], v11 offset:12288
	s_waitcnt lgkmcnt(14)
	v_mfma_f32_32x32x16_bf16 v[64:79], v[188:191], v[114:117], v[64:79]
	s_waitcnt lgkmcnt(13)
	v_mfma_f32_32x32x16_bf16 v[48:63], v[48:51], v[118:121], 0
	s_waitcnt lgkmcnt(12)
	v_mfma_f32_32x32x16_bf16 v[48:63], v[94:97], v[122:125], v[48:63]
	s_waitcnt lgkmcnt(11)
	v_mfma_f32_32x32x16_bf16 v[48:63], v[98:101], v[126:129], v[48:63]
	s_nop 5
	v_max3_f32 v163, v64, v65, v66
	v_max3_f32 v164, v72, v73, v74
	v_max3_f32 v163, v163, v67, v68
	v_max3_f32 v164, v164, v75, v76
	v_max3_f32 v163, v163, v69, v70
	v_max3_f32 v164, v164, v77, v78
	v_max3_f32 v163, v163, v71, v79
	s_waitcnt lgkmcnt(10)
	v_mfma_f32_32x32x16_bf16 v[48:63], v[102:105], v[130:133], v[48:63]
	v_max_f32_e32 v163, v163, v164
	v_mov_b32_e32 v164, v163
	s_nop 1
	v_permlane32_swap_b32_e32 v164, v163
	v_max_f32_e32 v163, v163, v164
	v_cmp_gt_f32_e32 vcc, v163, v162
	s_waitcnt lgkmcnt(9)
	v_mfma_f32_32x32x16_bf16 v[48:63], v[106:109], v[134:137], v[48:63]
	s_cbranch_vccnz .Lmla_rare0
.Lmla_back0:
	v_sub_f32_e32 v64, v64, v142
	v_sub_f32_e32 v65, v65, v142
	v_sub_f32_e32 v66, v66, v142
	v_sub_f32_e32 v67, v67, v142
	v_sub_f32_e32 v68, v68, v142
	v_sub_f32_e32 v69, v69, v142
	s_waitcnt lgkmcnt(8)
	v_mfma_f32_32x32x16_bf16 v[48:63], v[158:161], v[114:117], v[48:63]
	v_sub_f32_e32 v70, v70, v142
	v_sub_f32_e32 v71, v71, v142
	v_exp_f32_e32 v64, v64
	v_exp_f32_e32 v65, v65
	v_exp_f32_e32 v66, v66
	v_exp_f32_e32 v67, v67
	v_exp_f32_e32 v68, v68
	v_exp_f32_e32 v69, v69
	v_exp_f32_e32 v70, v70
	v_exp_f32_e32 v71, v71
	v_cvt_pk_bf16_f32 v196, v64, v65
	v_cvt_pk_bf16_f32 v197, v66, v67
	v_cvt_pk_bf16_f32 v198, v68, v69
	v_cvt_pk_bf16_f32 v199, v70, v71
	v_sub_f32_e32 v72, v72, v142
	v_sub_f32_e32 v73, v73, v142
	v_sub_f32_e32 v74, v74, v142
	v_sub_f32_e32 v75, v75, v142
	v_sub_f32_e32 v76, v76, v142
	v_sub_f32_e32 v77, v77, v142
	v_sub_f32_e32 v78, v78, v142
	v_sub_f32_e32 v79, v79, v142
	v_exp_f32_e32 v72, v72
	v_exp_f32_e32 v73, v73
	v_exp_f32_e32 v74, v74
	v_exp_f32_e32 v75, v75
	v_exp_f32_e32 v76, v76
	v_exp_f32_e32 v77, v77
	v_exp_f32_e32 v78, v78
	v_exp_f32_e32 v79, v79
	v_cvt_pk_bf16_f32 v200, v72, v73
	v_cvt_pk_bf16_f32 v201, v74, v75
	v_cvt_pk_bf16_f32 v202, v76, v77
	v_cvt_pk_bf16_f32 v203, v78, v79
	v_max3_f32 v163, v48, v49, v50
	v_max3_f32 v164, v56, v57, v58
	v_max3_f32 v163, v163, v51, v52
	v_max3_f32 v164, v164, v59, v60
	v_max3_f32 v163, v163, v53, v54
	v_max3_f32 v164, v164, v61, v62
	v_max3_f32 v163, v163, v55, v63
	v_max_f32_e32 v163, v163, v164
	v_mov_b32_e32 v164, v163
	s_nop 1
	v_permlane32_swap_b32_e32 v164, v163
	v_max_f32_e32 v163, v163, v164
	v_cmp_gt_f32_e32 vcc, v163, v162
	s_cbranch_vccnz .Lmla_rare1
; __device__ __forceinline__ float fast_exp2(float x) { return __builtin_amdgcn_exp2f(x); }
; template <int MODE>
; __device__ __forceinline__ void attn_unit(const Params& P, int b, int h, int qb, unsigned char* smem) {
;     ...
;       if (__any(mx > m_run + 24.0f)) {
;         const float m_new = fmaxf(m_run, mx);
;         const float alpha = fast_exp2(m_run - m_new);
;         m_run = m_new; l_run *= alpha;
;         const f32x2_t a2 = {alpha, alpha};
; #pragma unroll
;         for (int i = 0; i < 8; ++i) {
;           f32x2_t t0 = {oacc[0][2 * i], oacc[0][2 * i + 1]}, t1 = {oacc[1][2 * i], oacc[1][2 * i + 1]};
;           t0 *= a2; t1 *= a2;
;           oacc[0][2 * i] = t0[0]; oacc[0][2 * i + 1] = t0[1]; oacc[1][2 * i] = t1[0]; oacc[1][2 * i + 1] = t1[1];
;         }
;       }
;       {
;         const f32x2_t m2 = {m_run, m_run};
;         f32x2_t ps2 = {0.f, 0.f};
; #pragma unroll
;         for (int kb = 0; kb < 2; ++kb)
; #pragma unroll
;           for (int i = 0; i < 8; ++i) {
;             f32x2_t t = {sacc[kb][2 * i], sacc[kb][2 * i + 1]};
;             t -= m2;
;             f32x2_t e; e[0] = fast_exp2(t[0]); e[1] = fast_exp2(t[1]);
;             ps2 += e;
;             sacc[kb][2 * i] = e[0]; sacc[kb][2 * i + 1] = e[1];
;           }
;         l_run += ps2[0] + ps2[1];
;       }
;       bf16x8 pf[4];
; #pragma unroll
;       for (int a = 0; a < 4; ++a) {
;         const int kb = a >> 1, o8 = (a & 1) * 8;
;         u32x4 u;
;         u.x = pk_bf16(sacc[kb][o8 + 0], sacc[kb][o8 + 1]); u.y = pk_bf16(sacc[kb][o8 + 2], sacc[kb][o8 + 3]);
;         u.z = pk_bf16(sacc[kb][o8 + 4], sacc[kb][o8 + 5]); u.w = pk_bf16(sacc[kb][o8 + 6], sacc[kb][o8 + 7]);
;         pf[a] = __builtin_bit_cast(bf16x8, u);
;       }
; #pragma unroll
;       for (int db = 0; db < 2; ++db)
; #pragma unroll
;         for (int a = 0; a < 4; ++a) {
;           bf16x8 vf = *(const bf16x8*)(smem + cur + 8192 + (32 * db + r) * 128 + (((2 * a + hi) ^ swz) << 4));
;           oacc[db] = __builtin_amdgcn_mfma_f32_32x32x16_bf16(vf, pf[a], oacc[db], 0, 0, 0);
;         }
.Lmla_back1:
	s_waitcnt lgkmcnt(7)
	v_mfma_f32_32x32x16_bf16 v[32:47], v[212:215], v[196:199], v[32:47]
	v_sub_f32_e32 v48, v48, v142
	v_sub_f32_e32 v49, v49, v142
	v_sub_f32_e32 v50, v50, v142
	v_sub_f32_e32 v51, v51, v142
	v_sub_f32_e32 v52, v52, v142
	v_sub_f32_e32 v53, v53, v142
	v_sub_f32_e32 v54, v54, v142
	s_waitcnt lgkmcnt(6)
	v_mfma_f32_32x32x16_bf16 v[16:31], v[228:231], v[196:199], v[16:31]
	v_sub_f32_e32 v55, v55, v142
	v_exp_f32_e32 v48, v48
	v_exp_f32_e32 v49, v49
	v_exp_f32_e32 v50, v50
	s_waitcnt lgkmcnt(5)
	v_mfma_f32_32x32x16_bf16 v[32:47], v[216:219], v[200:203], v[32:47]
	v_exp_f32_e32 v51, v51
	v_exp_f32_e32 v52, v52
	v_exp_f32_e32 v53, v53
	v_exp_f32_e32 v54, v54
	s_waitcnt lgkmcnt(4)
	v_mfma_f32_32x32x16_bf16 v[16:31], v[232:235], v[200:203], v[16:31]
	v_exp_f32_e32 v55, v55
	v_cvt_pk_bf16_f32 v204, v48, v49
	v_cvt_pk_bf16_f32 v205, v50, v51
	v_cvt_pk_bf16_f32 v206, v52, v53
	v_cvt_pk_bf16_f32 v207, v54, v55
	v_sub_f32_e32 v56, v56, v142
	s_nop 0
	s_waitcnt lgkmcnt(3)
	v_mfma_f32_32x32x16_bf16 v[32:47], v[220:223], v[204:207], v[32:47]
	v_sub_f32_e32 v57, v57, v142
	v_sub_f32_e32 v58, v58, v142
	v_sub_f32_e32 v59, v59, v142
	v_sub_f32_e32 v60, v60, v142
	v_sub_f32_e32 v61, v61, v142
	v_sub_f32_e32 v62, v62, v142
	v_sub_f32_e32 v63, v63, v142
	s_waitcnt lgkmcnt(2)
	v_mfma_f32_32x32x16_bf16 v[16:31], v[236:239], v[204:207], v[16:31]
	v_exp_f32_e32 v56, v56
	v_exp_f32_e32 v57, v57
	v_exp_f32_e32 v58, v58
	v_exp_f32_e32 v59, v59
	v_exp_f32_e32 v60, v60
	v_exp_f32_e32 v61, v61
	v_exp_f32_e32 v62, v62
	v_exp_f32_e32 v63, v63
	v_cvt_pk_bf16_f32 v208, v56, v57
	v_cvt_pk_bf16_f32 v209, v58, v59
	v_cvt_pk_bf16_f32 v210, v60, v61
	v_cvt_pk_bf16_f32 v211, v62, v63
	s_nop 1
	s_waitcnt lgkmcnt(1)
	v_mfma_f32_32x32x16_bf16 v[32:47], v[224:227], v[208:211], v[32:47]
	v_add_f32_e32 v165, v64, v65
	v_add_f32_e32 v166, v66, v67
	v_add_f32_e32 v165, v165, v68
	v_add_f32_e32 v166, v166, v69
	v_add_f32_e32 v165, v165, v70
	v_add_f32_e32 v166, v166, v71
	v_add_f32_e32 v165, v165, v72
	s_waitcnt lgkmcnt(0)
	v_mfma_f32_32x32x16_bf16 v[16:31], v[240:243], v[208:211], v[16:31]
	v_add_f32_e32 v166, v166, v73
	v_add_f32_e32 v165, v165, v74
	v_add_f32_e32 v166, v166, v75
	v_add_f32_e32 v165, v165, v76
	v_add_f32_e32 v166, v166, v77
	v_add_f32_e32 v165, v165, v78
	v_add_f32_e32 v166, v166, v79
	v_add_f32_e32 v165, v165, v48
	v_add_f32_e32 v166, v166, v49
	v_add_f32_e32 v165, v165, v50
	v_add_f32_e32 v166, v166, v51
	v_add_f32_e32 v165, v165, v52
	v_add_f32_e32 v166, v166, v53
	v_add_f32_e32 v165, v165, v54
	v_add_f32_e32 v166, v166, v55
	v_add_f32_e32 v165, v165, v56
	v_add_f32_e32 v166, v166, v57
	v_add_f32_e32 v165, v165, v58
	v_add_f32_e32 v166, v166, v59
	v_add_f32_e32 v165, v165, v60
	v_add_f32_e32 v166, v166, v61
	v_add_f32_e32 v165, v165, v62
	v_add_f32_e32 v166, v166, v63
	v_add_f32_e32 v165, v165, v166
	v_add_f32_e32 v145, v145, v165
	s_branch .LBB0_854
.Lmla_rare0:
	v_max_f32_e32 v163, v163, v142
	v_sub_f32_e32 v167, v142, v163
	v_exp_f32_e32 v167, v167
	v_mov_b32_e32 v142, v163
	v_add_f32_e32 v162, 0x41c00000, v142
	v_mul_f32_e32 v145, v145, v167
	s_nop 11
	v_mul_f32_e32 v32, v32, v167
	v_mul_f32_e32 v33, v33, v167
	v_mul_f32_e32 v34, v34, v167
	v_mul_f32_e32 v35, v35, v167
	v_mul_f32_e32 v36, v36, v167
	v_mul_f32_e32 v37, v37, v167
	v_mul_f32_e32 v38, v38, v167
	v_mul_f32_e32 v39, v39, v167
	v_mul_f32_e32 v40, v40, v167
	v_mul_f32_e32 v41, v41, v167
	v_mul_f32_e32 v42, v42, v167
	v_mul_f32_e32 v43, v43, v167
	v_mul_f32_e32 v44, v44, v167
	v_mul_f32_e32 v45, v45, v167
	v_mul_f32_e32 v46, v46, v167
	v_mul_f32_e32 v47, v47, v167
	v_mul_f32_e32 v16, v16, v167
	v_mul_f32_e32 v17, v17, v167
	v_mul_f32_e32 v18, v18, v167
	v_mul_f32_e32 v19, v19, v167
	v_mul_f32_e32 v20, v20, v167
	v_mul_f32_e32 v21, v21, v167
	v_mul_f32_e32 v22, v22, v167
	v_mul_f32_e32 v23, v23, v167
	v_mul_f32_e32 v24, v24, v167
	v_mul_f32_e32 v25, v25, v167
	v_mul_f32_e32 v26, v26, v167
	v_mul_f32_e32 v27, v27, v167
	v_mul_f32_e32 v28, v28, v167
	v_mul_f32_e32 v29, v29, v167
	v_mul_f32_e32 v30, v30, v167
	v_mul_f32_e32 v31, v31, v167
	s_nop 1
	s_branch .Lmla_back0
.Lmla_rare1:
	v_max_f32_e32 v163, v163, v142
	v_sub_f32_e32 v167, v142, v163
	v_exp_f32_e32 v167, v167
	v_mov_b32_e32 v142, v163
	v_add_f32_e32 v162, 0x41c00000, v142
	v_mul_f32_e32 v145, v145, v167
	s_nop 11
	v_mul_f32_e32 v32, v32, v167
	v_mul_f32_e32 v33, v33, v167
	v_mul_f32_e32 v34, v34, v167
	v_mul_f32_e32 v35, v35, v167
	v_mul_f32_e32 v36, v36, v167
	v_mul_f32_e32 v37, v37, v167
	v_mul_f32_e32 v38, v38, v167
	v_mul_f32_e32 v39, v39, v167
	v_mul_f32_e32 v40, v40, v167
	v_mul_f32_e32 v41, v41, v167
	v_mul_f32_e32 v42, v42, v167
	v_mul_f32_e32 v43, v43, v167
	v_mul_f32_e32 v44, v44, v167
	v_mul_f32_e32 v45, v45, v167
	v_mul_f32_e32 v46, v46, v167
	v_mul_f32_e32 v47, v47, v167
	v_mul_f32_e32 v16, v16, v167
	v_mul_f32_e32 v17, v17, v167
	v_mul_f32_e32 v18, v18, v167
	v_mul_f32_e32 v19, v19, v167
	v_mul_f32_e32 v20, v20, v167
	v_mul_f32_e32 v21, v21, v167
	v_mul_f32_e32 v22, v22, v167
	v_mul_f32_e32 v23, v23, v167
	v_mul_f32_e32 v24, v24, v167
	v_mul_f32_e32 v25, v25, v167
	v_mul_f32_e32 v26, v26, v167
	v_mul_f32_e32 v27, v27, v167
	v_mul_f32_e32 v28, v28, v167
	v_mul_f32_e32 v29, v29, v167
	v_mul_f32_e32 v30, v30, v167
	v_mul_f32_e32 v31, v31, v167
	v_mul_f32_e32 v64, v64, v167
	v_mul_f32_e32 v65, v65, v167
	v_mul_f32_e32 v66, v66, v167
	v_mul_f32_e32 v67, v67, v167
	v_mul_f32_e32 v68, v68, v167
	v_mul_f32_e32 v69, v69, v167
	v_mul_f32_e32 v70, v70, v167
	v_mul_f32_e32 v71, v71, v167
	v_mul_f32_e32 v72, v72, v167
	v_mul_f32_e32 v73, v73, v167
	v_mul_f32_e32 v74, v74, v167
	v_mul_f32_e32 v75, v75, v167
	v_mul_f32_e32 v76, v76, v167
	v_mul_f32_e32 v77, v77, v167
	v_mul_f32_e32 v78, v78, v167
	v_mul_f32_e32 v79, v79, v167
	v_cvt_pk_bf16_f32 v196, v64, v65
	v_cvt_pk_bf16_f32 v197, v66, v67
	v_cvt_pk_bf16_f32 v198, v68, v69
	v_cvt_pk_bf16_f32 v199, v70, v71
	v_cvt_pk_bf16_f32 v200, v72, v73
	v_cvt_pk_bf16_f32 v201, v74, v75
	v_cvt_pk_bf16_f32 v202, v76, v77
	v_cvt_pk_bf16_f32 v203, v78, v79
	s_nop 1
	s_branch .Lmla_back1

; template <int MODE>
; __device__ __forceinline__ void attn_unit(const Params& P, int b, int h, int qb, unsigned char* smem) {
;     ...
;         if (MODE == 1) {
; #pragma unroll
;           for (int g = 0; g < 4; ++g) {
;             const f32x4 c4 = *(const f32x4*)(smem + cur + 20480 + (32 * kb + 8 * g + 4 * hi) * 4);
;             c0[4 * g] = c4[0]; c0[4 * g + 1] = c4[1]; c0[4 * g + 2] = c4[2]; c0[4 * g + 3] = c4[3];
;           }
;         } else {
; #pragma unroll
;           for (int i = 0; i < 16; ++i) c0[i] = 0.f;
;         }
;         sacc[kb] = c0;
; #pragma unroll
;         for (int ks = 0; ks < 4; ++ks) {
;           bf16x8 kf = *(const bf16x8*)(smem + cur + (32 * kb + r) * 128 + (((2 * ks + hi) ^ swz) << 4));
;           sacc[kb] = __builtin_amdgcn_mfma_f32_32x32x16_bf16(kf, qf[ks], sacc[kb], 0, 0, 0);
;         }
;         if (MODE == 0) {
; #pragma unroll
;           for (int ks = 0; ks < 2; ++ks) {
;             bf16x8 kf = *(const bf16x8*)(smem + cur + 16384 + (32 * kb + r) * 64 + (((2 * ks + hi) ^ swr) << 4));
;             sacc[kb] = __builtin_amdgcn_mfma_f32_32x32x16_bf16(kf, qf[4 + ks], sacc[kb], 0, 0, 0);
;           }
;         }
;       }
;       if (MODE == 2) {
; #pragma unroll
;         for (int kb = 0; kb < 2; ++kb)
; #pragma unroll
;           for (int i = 0; i < 16; ++i) {
;             const int key = k0 + 32 * kb + 8 * (i >> 2) + 4 * hi + (i & 3);
;             const int dist = qi - key;
;             const float v = sacc[kb][i] - slope2 * (float)dist;
;             sacc[kb][i] = (dist >= 0 && dist < 128) ? v : -INFINITY;
;           }
;       } else if (k0 + 63 > qw0) {
; #pragma unroll
;         for (int kb = 0; kb < 2; ++kb)
; #pragma unroll
;           for (int i = 0; i < 16; ++i) {
;             const int key = k0 + 32 * kb + 8 * (i >> 2) + 4 * hi + (i & 3);
;             if (key > qi) sacc[kb][i] = -INFINITY;
;           }
;       }
.LBB0_1618:
	s_or_b64 exec, exec, s[16:17]
	s_bitcmp1_b32 s8, 0
	s_cselect_b32 s24, 0x5100, 0
	s_sub_i32 s16, s21, 63
	v_cmp_le_i32_e32 vcc, s16, v84
	s_and_saveexec_b64 s[16:17], vcc
	s_cbranch_execz .LBB0_1624
	s_add_i32 s18, s24, 0
	v_add_u32_e32 v36, s18, v128
	v_add_u32_e32 v44, s18, v114
	v_add_u32_e32 v85, v36, v129
	v_add_u32_e32 v86, v36, v127
	v_add_u32_e32 v87, v36, v126
	v_add_u32_e32 v88, v36, v125
	ds_read_b128 v[48:51], v44 offset:20480
	ds_read_b128 v[52:55], v44 offset:20512
	ds_read_b128 v[56:59], v44 offset:20544
	ds_read_b128 v[60:63], v44 offset:20576
	ds_read_b128 v[160:163], v85
	ds_read_b128 v[164:167], v86
	ds_read_b128 v[168:171], v87
	ds_read_b128 v[172:175], v88
	ds_read_b128 v[90:93], v85 offset:4096
	ds_read_b128 v[130:133], v86 offset:4096
	ds_read_b128 v[134:137], v87 offset:4096
	ds_read_b128 v[138:141], v88 offset:4096
	v_cmp_gt_i32_e32 vcc, s21, v124
	s_cbranch_vccz .Lfox_fast
	s_waitcnt lgkmcnt(7)
	v_mfma_f32_32x32x16_bf16 v[48:63], v[160:163], v[100:103], v[48:63]
	ds_read_b128 v[32:35], v44 offset:20608
	ds_read_b128 v[36:39], v44 offset:20640
	ds_read_b128 v[40:43], v44 offset:20672
	ds_read_b128 v[44:47], v44 offset:20704
	s_waitcnt lgkmcnt(10)
	v_mfma_f32_32x32x16_bf16 v[48:63], v[164:167], v[104:107], v[48:63]
	s_waitcnt lgkmcnt(9)
	v_mfma_f32_32x32x16_bf16 v[48:63], v[168:171], v[108:111], v[48:63]
	s_waitcnt lgkmcnt(8)
	v_mfma_f32_32x32x16_bf16 v[48:63], v[172:175], v[96:99], v[48:63]
	s_waitcnt lgkmcnt(0)
	v_mfma_f32_32x32x16_bf16 v[32:47], v[90:93], v[100:103], v[32:47]
	v_mfma_f32_32x32x16_bf16 v[32:47], v[130:133], v[104:107], v[32:47]
	v_mfma_f32_32x32x16_bf16 v[32:47], v[134:137], v[108:111], v[32:47]
	v_mfma_f32_32x32x16_bf16 v[32:47], v[138:141], v[96:99], v[32:47]
	s_and_saveexec_b64 s[18:19], vcc
	s_cbranch_execz .LBB0_1621
	v_add_u32_e32 v89, s21, v121
	v_subrev_u32_e32 v90, 63, v89
	v_cmp_gt_i32_e32 vcc, v90, v120
	s_nop 1
	v_cndmask_b32_e32 v91, v48, v119, vcc
	v_cmp_lt_i32_e32 vcc, v90, v120
	v_subrev_u32_e32 v90, 61, v89
	s_nop 0
	v_cndmask_b32_e32 v48, v91, v48, vcc
	v_cndmask_b32_e32 v49, v119, v49, vcc
	v_cmp_le_i32_e32 vcc, v90, v120
	v_subrev_u32_e32 v90, 60, v89
	s_nop 0
	v_cndmask_b32_e32 v50, v119, v50, vcc
	v_cmp_le_i32_e32 vcc, v90, v120
	v_subrev_u32_e32 v90, 55, v89
	s_nop 0
	v_cndmask_b32_e32 v51, v119, v51, vcc
	v_cmp_le_i32_e32 vcc, v90, v120
	v_subrev_u32_e32 v90, 54, v89
	s_nop 0
	v_cndmask_b32_e32 v52, v119, v52, vcc
	v_cmp_le_i32_e32 vcc, v90, v120
	v_subrev_u32_e32 v90, 53, v89
	s_nop 0
	v_cndmask_b32_e32 v53, v119, v53, vcc
	v_cmp_le_i32_e32 vcc, v90, v120
	v_subrev_u32_e32 v90, 52, v89
	s_nop 0
	v_cndmask_b32_e32 v54, v119, v54, vcc
	v_cmp_le_i32_e32 vcc, v90, v120
	v_subrev_u32_e32 v90, 47, v89
	s_nop 0
	v_cndmask_b32_e32 v55, v119, v55, vcc
	v_cmp_le_i32_e32 vcc, v90, v120
	v_subrev_u32_e32 v90, 46, v89
	s_nop 0
	v_cndmask_b32_e32 v56, v119, v56, vcc
	v_cmp_le_i32_e32 vcc, v90, v120
	v_subrev_u32_e32 v90, 45, v89
	s_nop 0
	v_cndmask_b32_e32 v57, v119, v57, vcc
	v_cmp_le_i32_e32 vcc, v90, v120
	v_subrev_u32_e32 v90, 44, v89
	s_nop 0
	v_cndmask_b32_e32 v58, v119, v58, vcc
	v_cmp_le_i32_e32 vcc, v90, v120
	v_subrev_u32_e32 v90, 39, v89
	s_nop 0
	v_cndmask_b32_e32 v59, v119, v59, vcc
	v_cmp_le_i32_e32 vcc, v90, v120
	v_subrev_u32_e32 v90, 38, v89
	s_nop 0
	v_cndmask_b32_e32 v60, v119, v60, vcc
	v_cmp_le_i32_e32 vcc, v90, v120
	v_subrev_u32_e32 v90, 37, v89
	s_nop 0
	v_cndmask_b32_e32 v61, v119, v61, vcc
	v_cmp_le_i32_e32 vcc, v90, v120
	v_subrev_u32_e32 v90, 36, v89
	s_nop 0
	v_cndmask_b32_e32 v62, v119, v62, vcc
	v_cmp_le_i32_e32 vcc, v90, v120
	v_subrev_u32_e32 v90, 31, v89
	s_nop 0
	v_cndmask_b32_e32 v63, v119, v63, vcc
	v_cmp_le_i32_e32 vcc, v90, v120
	v_subrev_u32_e32 v90, 30, v89
	s_nop 0
	v_cndmask_b32_e32 v32, v119, v32, vcc
	v_cmp_le_i32_e32 vcc, v90, v120
	v_subrev_u32_e32 v90, 29, v89
	s_nop 0
	v_cndmask_b32_e32 v33, v119, v33, vcc
	v_cmp_le_i32_e32 vcc, v90, v120
	v_subrev_u32_e32 v90, 28, v89
	s_nop 0
	v_cndmask_b32_e32 v34, v119, v34, vcc
	v_cmp_le_i32_e32 vcc, v90, v120
	v_subrev_u32_e32 v90, 23, v89
	s_nop 0
	v_cndmask_b32_e32 v35, v119, v35, vcc
	v_cmp_le_i32_e32 vcc, v90, v120
	v_subrev_u32_e32 v90, 22, v89
	s_nop 0
	v_cndmask_b32_e32 v36, v119, v36, vcc
	v_cmp_le_i32_e32 vcc, v90, v120
	v_subrev_u32_e32 v90, 21, v89
	s_nop 0
	v_cndmask_b32_e32 v37, v119, v37, vcc
	v_cmp_le_i32_e32 vcc, v90, v120
	v_subrev_u32_e32 v90, 20, v89
	s_nop 0
	v_cndmask_b32_e32 v38, v119, v38, vcc
	v_cmp_le_i32_e32 vcc, v90, v120
	v_add_u32_e32 v90, -15, v89
	s_nop 0
	v_cndmask_b32_e32 v39, v119, v39, vcc
	v_cmp_le_i32_e32 vcc, v90, v120
	v_add_u32_e32 v90, -14, v89
	s_nop 0
	v_cndmask_b32_e32 v40, v119, v40, vcc
	v_cmp_le_i32_e32 vcc, v90, v120
	v_add_u32_e32 v90, -13, v89
	s_nop 0
	v_cndmask_b32_e32 v41, v119, v41, vcc
	v_cmp_le_i32_e32 vcc, v90, v120
	v_add_u32_e32 v90, -12, v89
	s_nop 0
	v_cndmask_b32_e32 v42, v119, v42, vcc
	v_cmp_le_i32_e32 vcc, v90, v120
	v_add_u32_e32 v90, -7, v89
	s_nop 0
	v_cndmask_b32_e32 v43, v119, v43, vcc
	v_cmp_le_i32_e32 vcc, v90, v120
	v_add_u32_e32 v90, -6, v89
	s_nop 0
	v_cndmask_b32_e32 v44, v119, v44, vcc
	v_cmp_le_i32_e32 vcc, v90, v120
	v_add_u32_e32 v90, -5, v89
	v_add_u32_e32 v89, -4, v89
	v_cndmask_b32_e32 v45, v119, v45, vcc
	v_cmp_le_i32_e32 vcc, v90, v120
	s_nop 1
	v_cndmask_b32_e32 v46, v119, v46, vcc
	v_cmp_le_i32_e32 vcc, v89, v120
	s_nop 1
	v_cndmask_b32_e32 v47, v119, v47, vcc

.Lfox_fast:
	v_add_f32_e32 v224, 0x41c00000, v118
	s_waitcnt lgkmcnt(7)
	v_mfma_f32_32x32x16_bf16 v[48:63], v[160:163], v[100:103], v[48:63]
	ds_read_b128 v[32:35], v44 offset:20608
	ds_read_b128 v[36:39], v44 offset:20640
	ds_read_b128 v[40:43], v44 offset:20672
	ds_read_b128 v[44:47], v44 offset:20704
	ds_read_b128 v[192:195], v85 offset:8192
	ds_read_b128 v[208:211], v85 offset:12288
	ds_read_b128 v[196:199], v86 offset:8192
	ds_read_b128 v[212:215], v86 offset:12288
	s_waitcnt lgkmcnt(14)
	v_mfma_f32_32x32x16_bf16 v[48:63], v[164:167], v[104:107], v[48:63]
	ds_read_b128 v[200:203], v87 offset:8192
	s_waitcnt lgkmcnt(14)
	v_mfma_f32_32x32x16_bf16 v[48:63], v[168:171], v[108:111], v[48:63]
	ds_read_b128 v[216:219], v87 offset:12288
	s_waitcnt lgkmcnt(14)
	v_mfma_f32_32x32x16_bf16 v[48:63], v[172:175], v[96:99], v[48:63]
	ds_read_b128 v[204:207], v88 offset:8192
	s_waitcnt lgkmcnt(7)
	v_mfma_f32_32x32x16_bf16 v[32:47], v[90:93], v[100:103], v[32:47]
	ds_read_b128 v[220:223], v88 offset:12288
	v_mfma_f32_32x32x16_bf16 v[32:47], v[130:133], v[104:107], v[32:47]
	s_nop 6
	v_max3_f32 v225, v48, v49, v50
	v_max3_f32 v226, v56, v57, v58
	v_max3_f32 v225, v225, v51, v52
	v_max3_f32 v226, v226, v59, v60
	v_max3_f32 v225, v225, v53, v54
	v_max3_f32 v226, v226, v61, v62
	v_max3_f32 v225, v225, v55, v63
	v_mfma_f32_32x32x16_bf16 v[32:47], v[134:137], v[108:111], v[32:47]
	v_max_f32_e32 v225, v225, v226
	v_mov_b32_e32 v226, v225
	s_nop 1
	v_permlane32_swap_b32_e32 v226, v225
	v_max_f32_e32 v225, v225, v226
	v_cmp_gt_f32_e32 vcc, v225, v224
	v_mfma_f32_32x32x16_bf16 v[32:47], v[138:141], v[96:99], v[32:47]
	s_cbranch_vccnz .Lfox_rare0
.Lfox_back0:
	v_sub_f32_e32 v48, v48, v118
	v_sub_f32_e32 v49, v49, v118
	v_sub_f32_e32 v50, v50, v118
	v_sub_f32_e32 v51, v51, v118
	v_sub_f32_e32 v52, v52, v118
	v_sub_f32_e32 v53, v53, v118
	v_sub_f32_e32 v54, v54, v118
	v_sub_f32_e32 v55, v55, v118
	v_exp_f32_e32 v48, v48
	v_exp_f32_e32 v49, v49
	v_exp_f32_e32 v50, v50
	v_exp_f32_e32 v51, v51
	v_exp_f32_e32 v52, v52
	v_exp_f32_e32 v53, v53
	v_exp_f32_e32 v54, v54
	v_exp_f32_e32 v55, v55
	v_cvt_pk_bf16_f32 v176, v48, v49
	v_cvt_pk_bf16_f32 v177, v50, v51
	v_cvt_pk_bf16_f32 v178, v52, v53
	v_cvt_pk_bf16_f32 v179, v54, v55
	v_sub_f32_e32 v56, v56, v118
	v_sub_f32_e32 v57, v57, v118
	v_sub_f32_e32 v58, v58, v118
	v_sub_f32_e32 v59, v59, v118
	v_sub_f32_e32 v60, v60, v118
	v_sub_f32_e32 v61, v61, v118
	v_sub_f32_e32 v62, v62, v118
	v_sub_f32_e32 v63, v63, v118
	v_exp_f32_e32 v56, v56
	v_exp_f32_e32 v57, v57
	v_exp_f32_e32 v58, v58
	v_exp_f32_e32 v59, v59
	v_exp_f32_e32 v60, v60
	v_exp_f32_e32 v61, v61
	v_exp_f32_e32 v62, v62
	v_exp_f32_e32 v63, v63
	v_cvt_pk_bf16_f32 v180, v56, v57
	v_cvt_pk_bf16_f32 v181, v58, v59
	v_cvt_pk_bf16_f32 v182, v60, v61
	v_cvt_pk_bf16_f32 v183, v62, v63
	v_max3_f32 v225, v32, v33, v34
	v_max3_f32 v226, v40, v41, v42
	v_max3_f32 v225, v225, v35, v36
	v_max3_f32 v226, v226, v43, v44
	v_max3_f32 v225, v225, v37, v38
	v_max3_f32 v226, v226, v45, v46
	v_max3_f32 v225, v225, v39, v47
	v_max_f32_e32 v225, v225, v226
	v_mov_b32_e32 v226, v225
	s_nop 1
	v_permlane32_swap_b32_e32 v226, v225
	v_max_f32_e32 v225, v225, v226
	v_cmp_gt_f32_e32 vcc, v225, v224
	s_cbranch_vccnz .Lfox_rare1
; __device__ __forceinline__ float fast_exp2(float x) { return __builtin_amdgcn_exp2f(x); }
; template <int MODE>
; __device__ __forceinline__ void attn_unit(const Params& P, int b, int h, int qb, unsigned char* smem) {
;     ...
;       if (__any(mx > m_run + 24.0f)) {
;         const float m_new = fmaxf(m_run, mx);
;         const float alpha = fast_exp2(m_run - m_new);
;         m_run = m_new; l_run *= alpha;
;         const f32x2_t a2 = {alpha, alpha};
; #pragma unroll
;         for (int i = 0; i < 8; ++i) {
;           f32x2_t t0 = {oacc[0][2 * i], oacc[0][2 * i + 1]}, t1 = {oacc[1][2 * i], oacc[1][2 * i + 1]};
;           t0 *= a2; t1 *= a2;
;           oacc[0][2 * i] = t0[0]; oacc[0][2 * i + 1] = t0[1]; oacc[1][2 * i] = t1[0]; oacc[1][2 * i + 1] = t1[1];
;         }
;       }
;       {
;         const f32x2_t m2 = {m_run, m_run};
;         f32x2_t ps2 = {0.f, 0.f};
; #pragma unroll
;         for (int kb = 0; kb < 2; ++kb)
; #pragma unroll
;           for (int i = 0; i < 8; ++i) {
;             f32x2_t t = {sacc[kb][2 * i], sacc[kb][2 * i + 1]};
;             t -= m2;
;             f32x2_t e; e[0] = fast_exp2(t[0]); e[1] = fast_exp2(t[1]);
;             ps2 += e;
;             sacc[kb][2 * i] = e[0]; sacc[kb][2 * i + 1] = e[1];
;           }
;         l_run += ps2[0] + ps2[1];
;       }
;       bf16x8 pf[4];
; #pragma unroll
;       for (int a = 0; a < 4; ++a) {
;         const int kb = a >> 1, o8 = (a & 1) * 8;
;         u32x4 u;
;         u.x = pk_bf16(sacc[kb][o8 + 0], sacc[kb][o8 + 1]); u.y = pk_bf16(sacc[kb][o8 + 2], sacc[kb][o8 + 3]);
;         u.z = pk_bf16(sacc[kb][o8 + 4], sacc[kb][o8 + 5]); u.w = pk_bf16(sacc[kb][o8 + 6], sacc[kb][o8 + 7]);
;         pf[a] = __builtin_bit_cast(bf16x8, u);
;       }
; #pragma unroll
;       for (int db = 0; db < 2; ++db)
; #pragma unroll
;         for (int a = 0; a < 4; ++a) {
;           bf16x8 vf = *(const bf16x8*)(smem + cur + 8192 + (32 * db + r) * 128 + (((2 * a + hi) ^ swz) << 4));
;           oacc[db] = __builtin_amdgcn_mfma_f32_32x32x16_bf16(vf, pf[a], oacc[db], 0, 0, 0);
;         }
.Lfox_back1:
	s_waitcnt lgkmcnt(7)
	v_mfma_f32_32x32x16_bf16 v[16:31], v[192:195], v[176:179], v[16:31]
	v_sub_f32_e32 v32, v32, v118
	v_sub_f32_e32 v33, v33, v118
	v_sub_f32_e32 v34, v34, v118
	v_sub_f32_e32 v35, v35, v118
	v_sub_f32_e32 v36, v36, v118
	v_sub_f32_e32 v37, v37, v118
	v_sub_f32_e32 v38, v38, v118
	s_waitcnt lgkmcnt(6)
	v_mfma_f32_32x32x16_bf16 v[0:15], v[208:211], v[176:179], v[0:15]
	v_sub_f32_e32 v39, v39, v118
	v_exp_f32_e32 v32, v32
	v_exp_f32_e32 v33, v33
	v_exp_f32_e32 v34, v34
	s_waitcnt lgkmcnt(5)
	v_mfma_f32_32x32x16_bf16 v[16:31], v[196:199], v[180:183], v[16:31]
	v_exp_f32_e32 v35, v35
	v_exp_f32_e32 v36, v36
	v_exp_f32_e32 v37, v37
	v_exp_f32_e32 v38, v38
	s_waitcnt lgkmcnt(4)
	v_mfma_f32_32x32x16_bf16 v[0:15], v[212:215], v[180:183], v[0:15]
	v_exp_f32_e32 v39, v39
	v_cvt_pk_bf16_f32 v184, v32, v33
	v_cvt_pk_bf16_f32 v185, v34, v35
	v_cvt_pk_bf16_f32 v186, v36, v37
	v_cvt_pk_bf16_f32 v187, v38, v39
	v_sub_f32_e32 v40, v40, v118
	s_nop 0
	s_waitcnt lgkmcnt(3)
	v_mfma_f32_32x32x16_bf16 v[16:31], v[200:203], v[184:187], v[16:31]
	v_sub_f32_e32 v41, v41, v118
	v_sub_f32_e32 v42, v42, v118
	v_sub_f32_e32 v43, v43, v118
	v_sub_f32_e32 v44, v44, v118
	v_sub_f32_e32 v45, v45, v118
	v_sub_f32_e32 v46, v46, v118
	v_sub_f32_e32 v47, v47, v118
	s_waitcnt lgkmcnt(2)
	v_mfma_f32_32x32x16_bf16 v[0:15], v[216:219], v[184:187], v[0:15]
	v_exp_f32_e32 v40, v40
	v_exp_f32_e32 v41, v41
	v_exp_f32_e32 v42, v42
	v_exp_f32_e32 v43, v43
	v_exp_f32_e32 v44, v44
	v_exp_f32_e32 v45, v45
	v_exp_f32_e32 v46, v46
	v_exp_f32_e32 v47, v47
	v_cvt_pk_bf16_f32 v188, v40, v41
	v_cvt_pk_bf16_f32 v189, v42, v43
	v_cvt_pk_bf16_f32 v190, v44, v45
	v_cvt_pk_bf16_f32 v191, v46, v47
	s_nop 1
	s_waitcnt lgkmcnt(1)
	v_mfma_f32_32x32x16_bf16 v[16:31], v[204:207], v[188:191], v[16:31]
	v_add_f32_e32 v227, v48, v49
	v_add_f32_e32 v228, v50, v51
	v_add_f32_e32 v227, v227, v52
	v_add_f32_e32 v228, v228, v53
	v_add_f32_e32 v227, v227, v54
	v_add_f32_e32 v228, v228, v55
	v_add_f32_e32 v227, v227, v56
	s_waitcnt lgkmcnt(0)
	v_mfma_f32_32x32x16_bf16 v[0:15], v[220:223], v[188:191], v[0:15]
	v_add_f32_e32 v228, v228, v57
	v_add_f32_e32 v227, v227, v58
	v_add_f32_e32 v228, v228, v59
	v_add_f32_e32 v227, v227, v60
	v_add_f32_e32 v228, v228, v61
	v_add_f32_e32 v227, v227, v62
	v_add_f32_e32 v228, v228, v63
	v_add_f32_e32 v227, v227, v32
	v_add_f32_e32 v228, v228, v33
	v_add_f32_e32 v227, v227, v34
	v_add_f32_e32 v228, v228, v35
	v_add_f32_e32 v227, v227, v36
	v_add_f32_e32 v228, v228, v37
	v_add_f32_e32 v227, v227, v38
	v_add_f32_e32 v228, v228, v39
	v_add_f32_e32 v227, v227, v40
	v_add_f32_e32 v228, v228, v41
	v_add_f32_e32 v227, v227, v42
	v_add_f32_e32 v228, v228, v43
	v_add_f32_e32 v227, v227, v44
	v_add_f32_e32 v228, v228, v45
	v_add_f32_e32 v227, v227, v46
	v_add_f32_e32 v228, v228, v47
	v_add_f32_e32 v227, v227, v228
	v_add_f32_e32 v123, v123, v227
	s_branch .LBB0_1624
.Lfox_rare0:
	v_max_f32_e32 v225, v225, v118
	v_sub_f32_e32 v229, v118, v225
	v_exp_f32_e32 v229, v229
	v_mov_b32_e32 v118, v225
	v_add_f32_e32 v224, 0x41c00000, v118
	v_mul_f32_e32 v123, v123, v229
	s_nop 11
	v_mul_f32_e32 v16, v16, v229
	v_mul_f32_e32 v17, v17, v229
	v_mul_f32_e32 v18, v18, v229
	v_mul_f32_e32 v19, v19, v229
	v_mul_f32_e32 v20, v20, v229
	v_mul_f32_e32 v21, v21, v229
	v_mul_f32_e32 v22, v22, v229
	v_mul_f32_e32 v23, v23, v229
	v_mul_f32_e32 v24, v24, v229
	v_mul_f32_e32 v25, v25, v229
	v_mul_f32_e32 v26, v26, v229
	v_mul_f32_e32 v27, v27, v229
	v_mul_f32_e32 v28, v28, v229
	v_mul_f32_e32 v29, v29, v229
	v_mul_f32_e32 v30, v30, v229
	v_mul_f32_e32 v31, v31, v229
	v_mul_f32_e32 v0, v0, v229
	v_mul_f32_e32 v1, v1, v229
	v_mul_f32_e32 v2, v2, v229
	v_mul_f32_e32 v3, v3, v229
	v_mul_f32_e32 v4, v4, v229
	v_mul_f32_e32 v5, v5, v229
	v_mul_f32_e32 v6, v6, v229
	v_mul_f32_e32 v7, v7, v229
	v_mul_f32_e32 v8, v8, v229
	v_mul_f32_e32 v9, v9, v229
	v_mul_f32_e32 v10, v10, v229
	v_mul_f32_e32 v11, v11, v229
	v_mul_f32_e32 v12, v12, v229
	v_mul_f32_e32 v13, v13, v229
	v_mul_f32_e32 v14, v14, v229
	v_mul_f32_e32 v15, v15, v229
	s_nop 1
	s_branch .Lfox_back0
.Lfox_rare1:
	v_max_f32_e32 v225, v225, v118
	v_sub_f32_e32 v229, v118, v225
	v_exp_f32_e32 v229, v229
	v_mov_b32_e32 v118, v225
	v_add_f32_e32 v224, 0x41c00000, v118
	v_mul_f32_e32 v123, v123, v229
	s_nop 11
	v_mul_f32_e32 v16, v16, v229
	v_mul_f32_e32 v17, v17, v229
	v_mul_f32_e32 v18, v18, v229
	v_mul_f32_e32 v19, v19, v229
	v_mul_f32_e32 v20, v20, v229
	v_mul_f32_e32 v21, v21, v229
	v_mul_f32_e32 v22, v22, v229
	v_mul_f32_e32 v23, v23, v229
	v_mul_f32_e32 v24, v24, v229
	v_mul_f32_e32 v25, v25, v229
	v_mul_f32_e32 v26, v26, v229
	v_mul_f32_e32 v27, v27, v229
	v_mul_f32_e32 v28, v28, v229
	v_mul_f32_e32 v29, v29, v229
	v_mul_f32_e32 v30, v30, v229
	v_mul_f32_e32 v31, v31, v229
	v_mul_f32_e32 v0, v0, v229
	v_mul_f32_e32 v1, v1, v229
	v_mul_f32_e32 v2, v2, v229
	v_mul_f32_e32 v3, v3, v229
	v_mul_f32_e32 v4, v4, v229
	v_mul_f32_e32 v5, v5, v229
	v_mul_f32_e32 v6, v6, v229
	v_mul_f32_e32 v7, v7, v229
	v_mul_f32_e32 v8, v8, v229
	v_mul_f32_e32 v9, v9, v229
	v_mul_f32_e32 v10, v10, v229
	v_mul_f32_e32 v11, v11, v229
	v_mul_f32_e32 v12, v12, v229
	v_mul_f32_e32 v13, v13, v229
	v_mul_f32_e32 v14, v14, v229
	v_mul_f32_e32 v15, v15, v229
	v_mul_f32_e32 v48, v48, v229
	v_mul_f32_e32 v49, v49, v229
	v_mul_f32_e32 v50, v50, v229
	v_mul_f32_e32 v51, v51, v229
	v_mul_f32_e32 v52, v52, v229
	v_mul_f32_e32 v53, v53, v229
	v_mul_f32_e32 v54, v54, v229
	v_mul_f32_e32 v55, v55, v229
	v_mul_f32_e32 v56, v56, v229
	v_mul_f32_e32 v57, v57, v229
	v_mul_f32_e32 v58, v58, v229
	v_mul_f32_e32 v59, v59, v229
	v_mul_f32_e32 v60, v60, v229
	v_mul_f32_e32 v61, v61, v229
	v_mul_f32_e32 v62, v62, v229
	v_mul_f32_e32 v63, v63, v229
	v_cvt_pk_bf16_f32 v176, v48, v49
	v_cvt_pk_bf16_f32 v177, v50, v51
	v_cvt_pk_bf16_f32 v178, v52, v53
	v_cvt_pk_bf16_f32 v179, v54, v55
	v_cvt_pk_bf16_f32 v180, v56, v57
	v_cvt_pk_bf16_f32 v181, v58, v59
	v_cvt_pk_bf16_f32 v182, v60, v61
	v_cvt_pk_bf16_f32 v183, v62, v63
	s_nop 1
	s_branch .Lfox_back1
